# add static s_setprio 1 for waves 4-7 during attention phases (on top of QK pipelining, counted vmcnt, epilogue load fix)
# speedup vs baseline: 1.0187x; 1.0187x over previous
.LBB0_935:
	s_cselect_b32 s100, 1, 0
	v_writelane_b32 v255, s100, 63
	v_readfirstlane_b32 s100, v198
	s_nop 1
	s_lshr_b32 s100, s100, 6
	s_cmp_lt_u32 s100, 4
	s_cbranch_scc1 .Lprio_attn
	s_setprio 1
.Lprio_attn:
	v_readlane_b32 s100, v255, 63
	s_nop 1
	s_cmp_lg_u32 s100, 0
	v_mov_b32_e32 v0, v198
	v_readlane_b32 s0, v252, 50
	s_nop 1
	v_add_u32_e32 v2, s0, v0
	s_movk_i32 s0, 0x2000
	v_cmp_gt_i32_e32 vcc, s0, v2
	s_and_saveexec_b64 s[0:1], vcc
	s_cbranch_execz .LBB0_937
	v_readlane_b32 s4, v252, 28
	v_ashrrev_i32_e32 v3, 31, v2
	v_readlane_b32 s5, v252, 29
	s_nop 1
	v_lshl_add_u64 v[2:3], v[2:3], 2, s[4:5]
	global_store_dword v[2:3], v1, off

.LBB0_1244:
	s_or_b64 exec, exec, s[0:1]
	s_andn2_b64 vcc, exec, s[22:23]
	s_movk_i32 s0, 0xa00
	s_waitcnt lgkmcnt(0)
	s_barrier
	s_setprio 0
	s_cbranch_vccnz .LBB0_1332
	s_cselect_b32 s100, 1, 0
	v_writelane_b32 v255, s100, 63
	v_readfirstlane_b32 s100, v198
	s_nop 1
	s_lshr_b32 s100, s100, 6
	s_cmp_lt_u32 s100, 4
	s_cbranch_scc1 .Lprio_dilb
	s_setprio 1
.Lprio_dilb:
	v_readlane_b32 s100, v255, 63
	s_nop 1
	s_cmp_lg_u32 s100, 0
	v_readlane_b32 s0, v253, 20
	v_readlane_b32 s1, v253, 21
	v_mov_b32_e32 v0, v198
	s_andn2_b64 vcc, exec, s[0:1]
	s_cbranch_vccnz .LBB0_1279
	v_ashrrev_i32_e32 v3, 6, v0
	v_and_b32_e32 v2, 31, v0
	v_lshlrev_b32_e32 v4, 5, v3
	v_lshrrev_b32_e32 v0, 3, v0
	v_and_or_b32 v0, v0, 4, v4
	s_movk_i32 s0, 0x1800
	v_mul_lo_u32 v0, v0, s0
	v_or_b32_e32 v5, v4, v2
	v_or_b32_e32 v146, v0, v2
	v_lshlrev_b32_e32 v179, 3, v5
	v_lshlrev_b32_e32 v194, 8, v3
	v_mov_b32_e32 v147, v1
	v_or_b32_e32 v148, 0x1800, v146
	v_mov_b32_e32 v149, v1
	v_or_b32_e32 v150, 0x1820, v146
	v_mov_b32_e32 v151, v1
	v_or_b32_e32 v152, 0x1840, v146
	v_mov_b32_e32 v153, v1
	v_or_b32_e32 v154, 0x1860, v146
	v_mov_b32_e32 v155, v1
	v_add_u32_e32 v156, 0x3000, v146
	v_mov_b32_e32 v157, v1
	v_add_u32_e32 v158, 0x4800, v146
	v_mov_b32_e32 v159, v1
	v_add_u32_e32 v160, 0xc000, v146
	v_mov_b32_e32 v161, v1
	v_add_u32_e32 v162, 0xd800, v146
	v_mov_b32_e32 v163, v1
	v_add_u32_e32 v164, 0xf000, v146
	v_mov_b32_e32 v165, v1
	v_add_u32_e32 v166, 0x10800, v146
	v_mov_b32_e32 v167, v1
	v_add_u32_e32 v168, 0x18000, v146
	v_mov_b32_e32 v169, v1
	v_add_u32_e32 v170, 0x19800, v146
	v_mov_b32_e32 v171, v1
	v_add_u32_e32 v172, 0x1b000, v146
	v_mov_b32_e32 v173, v1
	v_add_u32_e32 v174, 0x1c800, v146
	v_mov_b32_e32 v175, v1
	v_add_u32_e32 v176, 0x24000, v146
	v_mov_b32_e32 v177, v1
	v_add_u32_e32 v180, 0x25800, v146
	v_mov_b32_e32 v181, v1
	v_add_u32_e32 v182, 0x27000, v146
	v_mov_b32_e32 v183, v1
	v_add_u32_e32 v184, 0x28800, v146
	v_mov_b32_e32 v185, v1
	v_readlane_b32 s30, v253, 19
	s_branch .LBB0_1248

.LBB0_1331:
	s_or_b64 exec, exec, s[0:1]
	s_movk_i32 s0, 0x500
	s_waitcnt lgkmcnt(0)
	s_barrier
	s_setprio 0

	.amdhsa_kernel _Z8fwd_mega6Params
		.amdhsa_group_segment_fixed_size 0
		.amdhsa_private_segment_fixed_size 0
		.amdhsa_kernarg_size 528
		.amdhsa_user_sgpr_count 2
		.amdhsa_user_sgpr_dispatch_ptr 0
		.amdhsa_user_sgpr_queue_ptr 0
		.amdhsa_user_sgpr_kernarg_segment_ptr 1
		.amdhsa_user_sgpr_dispatch_id 0
		.amdhsa_user_sgpr_kernarg_preload_length 0
		.amdhsa_user_sgpr_kernarg_preload_offset 0
		.amdhsa_user_sgpr_private_segment_size 0
		.amdhsa_uses_dynamic_stack 0
		.amdhsa_enable_private_segment 0
		.amdhsa_system_sgpr_workgroup_id_x 1
		.amdhsa_system_sgpr_workgroup_id_y 0
		.amdhsa_system_sgpr_workgroup_id_z 0
		.amdhsa_system_sgpr_workgroup_info 0
		.amdhsa_system_vgpr_workitem_id 2
		.amdhsa_next_free_vgpr 256
		.amdhsa_next_free_sgpr 102
		.amdhsa_accum_offset 256
		.amdhsa_reserve_vcc 1
		.amdhsa_float_round_mode_32 0
		.amdhsa_float_round_mode_16_64 0
		.amdhsa_float_denorm_mode_32 3
		.amdhsa_float_denorm_mode_16_64 3
		.amdhsa_dx10_clamp 1
		.amdhsa_ieee_mode 1
		.amdhsa_fp16_overflow 0
		.amdhsa_tg_split 0
		.amdhsa_exception_fp_ieee_invalid_op 0
		.amdhsa_exception_fp_denorm_src 0
		.amdhsa_exception_fp_ieee_div_zero 0
		.amdhsa_exception_fp_ieee_overflow 0
		.amdhsa_exception_fp_ieee_underflow 0
		.amdhsa_exception_fp_ieee_inexact 0
		.amdhsa_exception_int_div_zero 0
	.end_amdhsa_kernel

amdhsa.kernels:
  - .agpr_count:     0
    .args:
      - .offset:         0
        .size:           272
        .value_kind:     by_value
      - .offset:         272
        .size:           4
        .value_kind:     hidden_block_count_x
      - .offset:         276
        .size:           4
        .value_kind:     hidden_block_count_y
      - .offset:         280
        .size:           4
        .value_kind:     hidden_block_count_z
      - .offset:         284
        .size:           2
        .value_kind:     hidden_group_size_x
      - .offset:         286
        .size:           2
        .value_kind:     hidden_group_size_y
      - .offset:         288
        .size:           2
        .value_kind:     hidden_group_size_z
      - .offset:         290
        .size:           2
        .value_kind:     hidden_remainder_x
      - .offset:         292
        .size:           2
        .value_kind:     hidden_remainder_y
      - .offset:         294
        .size:           2
        .value_kind:     hidden_remainder_z
      - .offset:         312
        .size:           8
        .value_kind:     hidden_global_offset_x
      - .offset:         320
        .size:           8
        .value_kind:     hidden_global_offset_y
      - .offset:         328
        .size:           8
        .value_kind:     hidden_global_offset_z
      - .offset:         336
        .size:           2
        .value_kind:     hidden_grid_dims
      - .offset:         360
        .size:           8
        .value_kind:     hidden_multigrid_sync_arg
      - .offset:         392
        .size:           4
        .value_kind:     hidden_dynamic_lds_size
    .group_segment_fixed_size: 0
    .kernarg_segment_align: 8
    .kernarg_segment_size: 528
    .language:       OpenCL C
    .language_version:
      - 2
      - 0
    .max_flat_workgroup_size: 512
    .name:           _Z8fwd_mega6Params
    .private_segment_fixed_size: 0
    .sgpr_count:     108
    .sgpr_spill_count: 275
    .symbol:         _Z8fwd_mega6Params.kd
    .uniform_work_group_size: 1
    .uses_dynamic_stack: false
    .vgpr_count:     256
    .vgpr_spill_count: 0
    .wavefront_size: 64
